# v105 + non-temporal stores for the FFN weight images written in the in-projection slot (first used 1.3 ms later)
# speedup vs baseline: 1.0077x; 1.0077x over previous
; #define LAS __attribute__((address_space(3)))
; __device__ __forceinline__ unsigned cvtpk(float lo, float hi) { f32x2_t v = {lo, hi}; bf16x2_t b = __builtin_convertvector(v, bf16x2_t); return __builtin_bit_cast(unsigned, b); }
; #define NTL(p) __builtin_nontemporal_load(&(p))
; __device__ __forceinline__ void tr_item(const float* W, int N, int K, int k0, int n0, bf16_t* dst, LAS float* scr, int lane) {
; #pragma unroll 8
;     for (int i = 0; i < 32; ++i) { const int kk = 2 * i + (lane >> 5); scr[kk * 33 + (lane & 31)] = NTL(W[(size_t)(k0 + kk) * N + n0 + (lane & 31)]); }
;     asm volatile("s_waitcnt lgkmcnt(0)" ::: "memory");
;     const int c = lane & 7;
; #pragma unroll
;     for (int j = 0; j < 4; ++j) { const int n = (lane >> 3) + 8 * j; const LAS float* s = scr + (8 * c) * 33 + n;
;         u32x4 o; o.x = cvtpk(s[0 * 33], s[1 * 33]); o.y = cvtpk(s[2 * 33], s[3 * 33]); o.z = cvtpk(s[4 * 33], s[5 * 33]); o.w = cvtpk(s[6 * 33], s[7 * 33]);
;         *(u32x4*)(dst + (size_t)n * K + k0 + 8 * c) = o; }
;     asm volatile("s_waitcnt lgkmcnt(0)" ::: "memory");
; }
; template <int PART>
; __device__ __forceinline__ void prologue(const Params& p, LAS unsigned char* lds, int G, int blk) {
;     ...
;         { const int kb = r / 64, nb = r % 64; tr_item(p.w_down, 2048, DFF, kb * 64, nb * 32, Wdn + (size_t)(nb * 32) * DFF, scr, lane); }
.LBB0_165:
	v_lshl_add_u64 v[72:73], v[40:41], 0, s[6:7]
	v_lshl_add_u64 v[74:75], v[38:39], 0, s[6:7]
	v_lshl_add_u64 v[76:77], v[36:37], 0, s[6:7]
	v_lshl_add_u64 v[78:79], v[34:35], 0, s[6:7]
	v_lshl_add_u64 v[80:81], v[32:33], 0, s[6:7]
	v_lshl_add_u64 v[82:83], v[30:31], 0, s[6:7]
	v_lshl_add_u64 v[84:85], v[28:29], 0, s[6:7]
	v_lshl_add_u64 v[86:87], v[26:27], 0, s[6:7]
	global_load_dword v112, v[72:73], off nt
	global_load_dword v113, v[74:75], off nt
	global_load_dword v114, v[76:77], off nt
	global_load_dword v115, v[78:79], off nt
	global_load_dword v116, v[80:81], off nt
	global_load_dword v117, v[82:83], off nt
	global_load_dword v118, v[84:85], off nt
	global_load_dword v119, v[86:87], off nt
	s_add_u32 s6, s6, 0x20000
	s_addc_u32 s7, s7, 0
	v_lshl_add_u64 v[72:73], v[40:41], 0, s[6:7]
	v_lshl_add_u64 v[74:75], v[38:39], 0, s[6:7]
	v_lshl_add_u64 v[76:77], v[36:37], 0, s[6:7]
	v_lshl_add_u64 v[78:79], v[34:35], 0, s[6:7]
	v_lshl_add_u64 v[80:81], v[32:33], 0, s[6:7]
	v_lshl_add_u64 v[82:83], v[30:31], 0, s[6:7]
	v_lshl_add_u64 v[84:85], v[28:29], 0, s[6:7]
	v_lshl_add_u64 v[86:87], v[26:27], 0, s[6:7]
	global_load_dword v120, v[72:73], off nt
	global_load_dword v121, v[74:75], off nt
	global_load_dword v122, v[76:77], off nt
	global_load_dword v123, v[78:79], off nt
	global_load_dword v124, v[80:81], off nt
	global_load_dword v125, v[82:83], off nt
	global_load_dword v126, v[84:85], off nt
	global_load_dword v127, v[86:87], off nt
	s_add_u32 s6, s6, 0x20000
	s_addc_u32 s7, s7, 0
	v_lshl_add_u64 v[72:73], v[40:41], 0, s[6:7]
	v_lshl_add_u64 v[74:75], v[38:39], 0, s[6:7]
	v_lshl_add_u64 v[76:77], v[36:37], 0, s[6:7]
	v_lshl_add_u64 v[78:79], v[34:35], 0, s[6:7]
	v_lshl_add_u64 v[80:81], v[32:33], 0, s[6:7]
	v_lshl_add_u64 v[82:83], v[30:31], 0, s[6:7]
	v_lshl_add_u64 v[84:85], v[28:29], 0, s[6:7]
	v_lshl_add_u64 v[86:87], v[26:27], 0, s[6:7]
	global_load_dword v128, v[72:73], off nt
	global_load_dword v129, v[74:75], off nt
	global_load_dword v130, v[76:77], off nt
	global_load_dword v131, v[78:79], off nt
	global_load_dword v132, v[80:81], off nt
	global_load_dword v133, v[82:83], off nt
	global_load_dword v134, v[84:85], off nt
	global_load_dword v135, v[86:87], off nt
	s_add_u32 s6, s6, 0x20000
	s_addc_u32 s7, s7, 0
	v_lshl_add_u64 v[72:73], v[40:41], 0, s[6:7]
	v_lshl_add_u64 v[74:75], v[38:39], 0, s[6:7]
	v_lshl_add_u64 v[76:77], v[36:37], 0, s[6:7]
	v_lshl_add_u64 v[78:79], v[34:35], 0, s[6:7]
	v_lshl_add_u64 v[80:81], v[32:33], 0, s[6:7]
	v_lshl_add_u64 v[82:83], v[30:31], 0, s[6:7]
	v_lshl_add_u64 v[84:85], v[28:29], 0, s[6:7]
	v_lshl_add_u64 v[86:87], v[26:27], 0, s[6:7]
	global_load_dword v136, v[72:73], off nt
	global_load_dword v137, v[74:75], off nt
	global_load_dword v138, v[76:77], off nt
	global_load_dword v139, v[78:79], off nt
	global_load_dword v140, v[80:81], off nt
	global_load_dword v141, v[82:83], off nt
	global_load_dword v142, v[84:85], off nt
	global_load_dword v143, v[86:87], off nt
	s_add_u32 s6, s6, 0x20000
	s_addc_u32 s7, s7, 0
	v_add_u32_e32 v78, 0x400, v2
	s_waitcnt vmcnt(30)
	ds_write2_b32 v2, v112, v113 offset1:66
	s_waitcnt vmcnt(28)
	ds_write2_b32 v2, v114, v115 offset0:132 offset1:198
	s_waitcnt vmcnt(26)
	ds_write2_b32 v78, v116, v117 offset0:8 offset1:74
	s_waitcnt vmcnt(24)
	ds_write2_b32 v78, v118, v119 offset0:140 offset1:206
	v_add_u32_e32 v2, 0x840, v2
	v_add_u32_e32 v78, 0x400, v2
	s_waitcnt vmcnt(22)
	ds_write2_b32 v2, v120, v121 offset1:66
	s_waitcnt vmcnt(20)
	ds_write2_b32 v2, v122, v123 offset0:132 offset1:198
	s_waitcnt vmcnt(18)
	ds_write2_b32 v78, v124, v125 offset0:8 offset1:74
	s_waitcnt vmcnt(16)
	ds_write2_b32 v78, v126, v127 offset0:140 offset1:206
	v_add_u32_e32 v2, 0x840, v2
	v_add_u32_e32 v78, 0x400, v2
	s_waitcnt vmcnt(14)
	ds_write2_b32 v2, v128, v129 offset1:66
	s_waitcnt vmcnt(12)
	ds_write2_b32 v2, v130, v131 offset0:132 offset1:198
	s_waitcnt vmcnt(10)
	ds_write2_b32 v78, v132, v133 offset0:8 offset1:74
	s_waitcnt vmcnt(8)
	ds_write2_b32 v78, v134, v135 offset0:140 offset1:206
	v_add_u32_e32 v2, 0x840, v2
	v_add_u32_e32 v78, 0x400, v2
	s_waitcnt vmcnt(6)
	ds_write2_b32 v2, v136, v137 offset1:66
	s_waitcnt vmcnt(4)
	ds_write2_b32 v2, v138, v139 offset0:132 offset1:198
	s_waitcnt vmcnt(2)
	ds_write2_b32 v78, v140, v141 offset0:8 offset1:74
	s_waitcnt vmcnt(0)
	ds_write2_b32 v78, v142, v143 offset0:140 offset1:206
	v_add_u32_e32 v2, 0x840, v2
	s_lshl_b32 s6, s0, 5
	s_and_b32 s4, s0, 0x7fffffc0
	s_and_b32 s6, s6, 0x7e0
	s_addk_i32 s4, 0x9c00
	s_mulk_i32 s6, 0x2c00
	s_waitcnt lgkmcnt(0)
	s_add_u32 s14, s17, s6
	ds_read2_b32 v[30:31], v5 offset0:33 offset1:41
	ds_read2_b32 v[32:33], v5 offset1:8
	ds_read2_b32 v[34:35], v5 offset0:66 offset1:74
	ds_read2_b32 v[36:37], v5 offset0:99 offset1:107
	ds_read2_b32 v[38:39], v5 offset0:132 offset1:140
	ds_read2_b32 v[40:41], v5 offset0:165 offset1:173
	ds_read2_b32 v[72:73], v5 offset0:198 offset1:206
	ds_read2_b32 v[74:75], v5 offset0:231 offset1:239
	s_addc_u32 s15, s22, 0
	s_lshl_b64 s[6:7], s[4:5], 1
	s_add_u32 s6, s14, s6
	s_addc_u32 s7, s15, s7
	v_lshlrev_b32_e32 v2, 1, v0
	v_lshl_add_u64 v[76:77], s[6:7], 0, v[2:3]
	v_mov_b32_e32 v25, v3
	s_waitcnt lgkmcnt(6)
	v_cvt_pk_bf16_f32 v26, v32, v30
	s_waitcnt lgkmcnt(4)
	v_cvt_pk_bf16_f32 v27, v34, v36
	s_waitcnt lgkmcnt(2)
	v_cvt_pk_bf16_f32 v28, v38, v40
	s_waitcnt lgkmcnt(0)
	v_cvt_pk_bf16_f32 v29, v72, v74
	v_lshl_add_u64 v[76:77], v[76:77], 0, v[24:25]
	global_store_dwordx4 v[76:77], v[26:29], off nt
	v_add_co_u32_e32 v30, vcc, s26, v76
	s_nop 0
	v_cvt_pk_bf16_f32 v26, v33, v31
	v_cvt_pk_bf16_f32 v27, v35, v37
	v_cvt_pk_bf16_f32 v28, v39, v41
	v_cvt_pk_bf16_f32 v29, v73, v75
	ds_read2_b32 v[32:33], v5 offset0:49 offset1:57
	ds_read2_b32 v[34:35], v5 offset0:16 offset1:24
	ds_read2_b32 v[36:37], v5 offset0:82 offset1:90
	ds_read2_b32 v[38:39], v5 offset0:115 offset1:123
	ds_read2_b32 v[40:41], v5 offset0:148 offset1:156
	ds_read2_b32 v[72:73], v5 offset0:181 offset1:189
	ds_read2_b32 v[74:75], v5 offset0:214 offset1:222
	ds_read2_b32 v[78:79], v5 offset0:247 offset1:255
	v_addc_co_u32_e32 v31, vcc, 0, v77, vcc
	global_store_dwordx4 v[30:31], v[26:29], off nt
	v_add_co_u32_e32 v30, vcc, s27, v76
	s_waitcnt lgkmcnt(6)
	v_cvt_pk_bf16_f32 v26, v34, v32
	s_waitcnt lgkmcnt(4)
	v_cvt_pk_bf16_f32 v27, v36, v38
	s_waitcnt lgkmcnt(2)
	v_cvt_pk_bf16_f32 v28, v40, v72
	s_waitcnt lgkmcnt(0)
	v_cvt_pk_bf16_f32 v29, v74, v78
	v_addc_co_u32_e32 v31, vcc, 0, v77, vcc
	global_store_dwordx4 v[30:31], v[26:29], off nt
	v_add_co_u32_e32 v30, vcc, 0x42000, v76
	s_nop 0
	v_cvt_pk_bf16_f32 v26, v35, v33
	v_cvt_pk_bf16_f32 v27, v37, v39
	v_cvt_pk_bf16_f32 v28, v41, v73
	v_cvt_pk_bf16_f32 v29, v75, v79
	v_addc_co_u32_e32 v31, vcc, 0, v77, vcc
	global_store_dwordx4 v[30:31], v[26:29], off nt
	s_waitcnt lgkmcnt(0)
	s_mov_b64 s[6:7], 0

; #define LAS __attribute__((address_space(3)))
; __device__ __forceinline__ unsigned cvtpk(float lo, float hi) { f32x2_t v = {lo, hi}; bf16x2_t b = __builtin_convertvector(v, bf16x2_t); return __builtin_bit_cast(unsigned, b); }
; #define NTL(p) __builtin_nontemporal_load(&(p))
; __device__ __forceinline__ void tr_item(const float* W, int N, int K, int k0, int n0, bf16_t* dst, LAS float* scr, int lane) {
; #pragma unroll 8
;     for (int i = 0; i < 32; ++i) { const int kk = 2 * i + (lane >> 5); scr[kk * 33 + (lane & 31)] = NTL(W[(size_t)(k0 + kk) * N + n0 + (lane & 31)]); }
;     asm volatile("s_waitcnt lgkmcnt(0)" ::: "memory");
;     const int c = lane & 7;
; #pragma unroll
;     for (int j = 0; j < 4; ++j) { const int n = (lane >> 3) + 8 * j; const LAS float* s = scr + (8 * c) * 33 + n;
;         u32x4 o; o.x = cvtpk(s[0 * 33], s[1 * 33]); o.y = cvtpk(s[2 * 33], s[3 * 33]); o.z = cvtpk(s[4 * 33], s[5 * 33]); o.w = cvtpk(s[6 * 33], s[7 * 33]);
;         *(u32x4*)(dst + (size_t)n * K + k0 + 8 * c) = o; }
;     asm volatile("s_waitcnt lgkmcnt(0)" ::: "memory");
; }
; template <int PART>
; __device__ __forceinline__ void prologue(const Params& p, LAS unsigned char* lds, int G, int blk) {
;     ...
;         if (r < I4) { const int kb = r / 352, nb = r % 352, n0 = nb * 32; int drow;
;             if (n0 < DFF) drow = 256 * (n0 / 128) + (n0 % 128); else { const int c2 = n0 - DFF; drow = 256 * (c2 / 128) + 128 + (c2 % 128); }
;             tr_item(p.w_gu, 2 * DFF, 2048, kb * 64, n0, Wgu + (size_t)drow * 2048, scr, lane); continue; }
.LBB0_173:
	v_lshl_add_u64 v[72:73], v[40:41], 0, s[18:19]
	v_lshl_add_u64 v[74:75], v[38:39], 0, s[18:19]
	v_lshl_add_u64 v[76:77], v[36:37], 0, s[18:19]
	v_lshl_add_u64 v[78:79], v[34:35], 0, s[18:19]
	v_lshl_add_u64 v[80:81], v[32:33], 0, s[18:19]
	v_lshl_add_u64 v[82:83], v[30:31], 0, s[18:19]
	v_lshl_add_u64 v[84:85], v[28:29], 0, s[18:19]
	v_lshl_add_u64 v[86:87], v[26:27], 0, s[18:19]
	global_load_dword v112, v[72:73], off nt
	global_load_dword v113, v[74:75], off nt
	global_load_dword v114, v[76:77], off nt
	global_load_dword v115, v[78:79], off nt
	global_load_dword v116, v[80:81], off nt
	global_load_dword v117, v[82:83], off nt
	global_load_dword v118, v[84:85], off nt
	global_load_dword v119, v[86:87], off nt
	s_add_u32 s18, s18, 0xb0000
	s_addc_u32 s19, s19, 0
	v_lshl_add_u64 v[72:73], v[40:41], 0, s[18:19]
	v_lshl_add_u64 v[74:75], v[38:39], 0, s[18:19]
	v_lshl_add_u64 v[76:77], v[36:37], 0, s[18:19]
	v_lshl_add_u64 v[78:79], v[34:35], 0, s[18:19]
	v_lshl_add_u64 v[80:81], v[32:33], 0, s[18:19]
	v_lshl_add_u64 v[82:83], v[30:31], 0, s[18:19]
	v_lshl_add_u64 v[84:85], v[28:29], 0, s[18:19]
	v_lshl_add_u64 v[86:87], v[26:27], 0, s[18:19]
	global_load_dword v120, v[72:73], off nt
	global_load_dword v121, v[74:75], off nt
	global_load_dword v122, v[76:77], off nt
	global_load_dword v123, v[78:79], off nt
	global_load_dword v124, v[80:81], off nt
	global_load_dword v125, v[82:83], off nt
	global_load_dword v126, v[84:85], off nt
	global_load_dword v127, v[86:87], off nt
	s_add_u32 s18, s18, 0xb0000
	s_addc_u32 s19, s19, 0
	v_lshl_add_u64 v[72:73], v[40:41], 0, s[18:19]
	v_lshl_add_u64 v[74:75], v[38:39], 0, s[18:19]
	v_lshl_add_u64 v[76:77], v[36:37], 0, s[18:19]
	v_lshl_add_u64 v[78:79], v[34:35], 0, s[18:19]
	v_lshl_add_u64 v[80:81], v[32:33], 0, s[18:19]
	v_lshl_add_u64 v[82:83], v[30:31], 0, s[18:19]
	v_lshl_add_u64 v[84:85], v[28:29], 0, s[18:19]
	v_lshl_add_u64 v[86:87], v[26:27], 0, s[18:19]
	global_load_dword v128, v[72:73], off nt
	global_load_dword v129, v[74:75], off nt
	global_load_dword v130, v[76:77], off nt
	global_load_dword v131, v[78:79], off nt
	global_load_dword v132, v[80:81], off nt
	global_load_dword v133, v[82:83], off nt
	global_load_dword v134, v[84:85], off nt
	global_load_dword v135, v[86:87], off nt
	s_add_u32 s18, s18, 0xb0000
	s_addc_u32 s19, s19, 0
	v_lshl_add_u64 v[72:73], v[40:41], 0, s[18:19]
	v_lshl_add_u64 v[74:75], v[38:39], 0, s[18:19]
	v_lshl_add_u64 v[76:77], v[36:37], 0, s[18:19]
	v_lshl_add_u64 v[78:79], v[34:35], 0, s[18:19]
	v_lshl_add_u64 v[80:81], v[32:33], 0, s[18:19]
	v_lshl_add_u64 v[82:83], v[30:31], 0, s[18:19]
	v_lshl_add_u64 v[84:85], v[28:29], 0, s[18:19]
	v_lshl_add_u64 v[86:87], v[26:27], 0, s[18:19]
	global_load_dword v136, v[72:73], off nt
	global_load_dword v137, v[74:75], off nt
	global_load_dword v138, v[76:77], off nt
	global_load_dword v139, v[78:79], off nt
	global_load_dword v140, v[80:81], off nt
	global_load_dword v141, v[82:83], off nt
	global_load_dword v142, v[84:85], off nt
	global_load_dword v143, v[86:87], off nt
	s_add_u32 s18, s18, 0xb0000
	s_addc_u32 s19, s19, 0
	v_add_u32_e32 v78, 0x400, v2
	s_waitcnt vmcnt(30)
	ds_write2_b32 v2, v112, v113 offset1:66
	s_waitcnt vmcnt(28)
	ds_write2_b32 v2, v114, v115 offset0:132 offset1:198
	s_waitcnt vmcnt(26)
	ds_write2_b32 v78, v116, v117 offset0:8 offset1:74
	s_waitcnt vmcnt(24)
	ds_write2_b32 v78, v118, v119 offset0:140 offset1:206
	v_add_u32_e32 v2, 0x840, v2
	v_add_u32_e32 v78, 0x400, v2
	s_waitcnt vmcnt(22)
	ds_write2_b32 v2, v120, v121 offset1:66
	s_waitcnt vmcnt(20)
	ds_write2_b32 v2, v122, v123 offset0:132 offset1:198
	s_waitcnt vmcnt(18)
	ds_write2_b32 v78, v124, v125 offset0:8 offset1:74
	s_waitcnt vmcnt(16)
	ds_write2_b32 v78, v126, v127 offset0:140 offset1:206
	v_add_u32_e32 v2, 0x840, v2
	v_add_u32_e32 v78, 0x400, v2
	s_waitcnt vmcnt(14)
	ds_write2_b32 v2, v128, v129 offset1:66
	s_waitcnt vmcnt(12)
	ds_write2_b32 v2, v130, v131 offset0:132 offset1:198
	s_waitcnt vmcnt(10)
	ds_write2_b32 v78, v132, v133 offset0:8 offset1:74
	s_waitcnt vmcnt(8)
	ds_write2_b32 v78, v134, v135 offset0:140 offset1:206
	v_add_u32_e32 v2, 0x840, v2
	v_add_u32_e32 v78, 0x400, v2
	s_waitcnt vmcnt(6)
	ds_write2_b32 v2, v136, v137 offset1:66
	s_waitcnt vmcnt(4)
	ds_write2_b32 v2, v138, v139 offset0:132 offset1:198
	s_waitcnt vmcnt(2)
	ds_write2_b32 v78, v140, v141 offset0:8 offset1:74
	s_waitcnt vmcnt(0)
	ds_write2_b32 v78, v142, v143 offset0:140 offset1:206
	v_add_u32_e32 v2, 0x840, v2
	s_mov_b32 s7, s5
	s_lshl_b64 s[6:7], s[6:7], 12
	s_add_u32 s4, s3, s6
	s_waitcnt lgkmcnt(0)
	s_addc_u32 s7, s16, s7
	s_and_b32 s6, 0xffff, s14
	ds_read2_b32 v[30:31], v5 offset0:33 offset1:41
	ds_read2_b32 v[32:33], v5 offset1:8
	ds_read2_b32 v[34:35], v5 offset0:66 offset1:74
	ds_read2_b32 v[36:37], v5 offset0:99 offset1:107
	ds_read2_b32 v[38:39], v5 offset0:132 offset1:140
	ds_read2_b32 v[40:41], v5 offset0:165 offset1:173
	ds_read2_b32 v[72:73], v5 offset0:198 offset1:206
	ds_read2_b32 v[74:75], v5 offset0:231 offset1:239
	s_lshl_b32 s6, s6, 1
	s_add_u32 s6, s4, s6
	s_addc_u32 s7, s7, 0
	v_lshlrev_b32_e32 v2, 1, v0
	v_lshl_add_u64 v[76:77], s[6:7], 0, v[2:3]
	v_lshlrev_b32_e32 v2, 1, v4
	s_waitcnt lgkmcnt(6)
	v_cvt_pk_bf16_f32 v26, v32, v30
	s_waitcnt lgkmcnt(4)
	v_cvt_pk_bf16_f32 v27, v34, v36
	s_waitcnt lgkmcnt(2)
	v_cvt_pk_bf16_f32 v28, v38, v40
	s_waitcnt lgkmcnt(0)
	v_cvt_pk_bf16_f32 v29, v72, v74
	v_lshl_add_u64 v[78:79], v[76:77], 0, v[2:3]
	global_store_dwordx4 v[78:79], v[26:29], off nt
	v_lshlrev_b32_e32 v2, 1, v6
	s_mov_b64 s[6:7], 0
	v_cvt_pk_bf16_f32 v26, v33, v31
	v_cvt_pk_bf16_f32 v27, v35, v37
	v_cvt_pk_bf16_f32 v28, v39, v41
	v_cvt_pk_bf16_f32 v29, v73, v75
	ds_read2_b32 v[32:33], v5 offset0:49 offset1:57
	ds_read2_b32 v[34:35], v5 offset0:16 offset1:24
	ds_read2_b32 v[36:37], v5 offset0:82 offset1:90
	ds_read2_b32 v[38:39], v5 offset0:115 offset1:123
	ds_read2_b32 v[40:41], v5 offset0:148 offset1:156
	ds_read2_b32 v[72:73], v5 offset0:181 offset1:189
	ds_read2_b32 v[74:75], v5 offset0:214 offset1:222
	ds_read2_b32 v[78:79], v5 offset0:247 offset1:255
	v_lshl_add_u64 v[30:31], v[76:77], 0, v[2:3]
	v_lshlrev_b32_e32 v2, 1, v8
	global_store_dwordx4 v[30:31], v[26:29], off nt
	v_lshl_add_u64 v[30:31], v[76:77], 0, v[2:3]
	v_lshlrev_b32_e32 v2, 1, v10
	s_waitcnt lgkmcnt(6)
	v_cvt_pk_bf16_f32 v26, v34, v32
	s_waitcnt lgkmcnt(4)
	v_cvt_pk_bf16_f32 v27, v36, v38
	s_waitcnt lgkmcnt(2)
	v_cvt_pk_bf16_f32 v28, v40, v72
	s_waitcnt lgkmcnt(0)
	v_cvt_pk_bf16_f32 v29, v74, v78
	global_store_dwordx4 v[30:31], v[26:29], off nt
	v_lshl_add_u64 v[30:31], v[76:77], 0, v[2:3]
	s_nop 0
	v_cvt_pk_bf16_f32 v26, v35, v33
	v_cvt_pk_bf16_f32 v27, v37, v39
	v_cvt_pk_bf16_f32 v28, v41, v73
	v_cvt_pk_bf16_f32 v29, v75, v79
	global_store_dwordx4 v[30:31], v[26:29], off nt
	s_waitcnt lgkmcnt(0)

; #define LAS __attribute__((address_space(3)))
; __device__ __forceinline__ unsigned cvtpk(float lo, float hi) { f32x2_t v = {lo, hi}; bf16x2_t b = __builtin_convertvector(v, bf16x2_t); return __builtin_bit_cast(unsigned, b); }
; #define NTL(p) __builtin_nontemporal_load(&(p))
; __device__ __forceinline__ void tr_item(const float* W, int N, int K, int k0, int n0, bf16_t* dst, LAS float* scr, int lane) {
; #pragma unroll 8
;     for (int i = 0; i < 32; ++i) { const int kk = 2 * i + (lane >> 5); scr[kk * 33 + (lane & 31)] = NTL(W[(size_t)(k0 + kk) * N + n0 + (lane & 31)]); }
;     asm volatile("s_waitcnt lgkmcnt(0)" ::: "memory");
;     const int c = lane & 7;
; #pragma unroll
;     for (int j = 0; j < 4; ++j) { const int n = (lane >> 3) + 8 * j; const LAS float* s = scr + (8 * c) * 33 + n;
;         u32x4 o; o.x = cvtpk(s[0 * 33], s[1 * 33]); o.y = cvtpk(s[2 * 33], s[3 * 33]); o.z = cvtpk(s[4 * 33], s[5 * 33]); o.w = cvtpk(s[6 * 33], s[7 * 33]);
;         *(u32x4*)(dst + (size_t)n * K + k0 + 8 * c) = o; }
;     asm volatile("s_waitcnt lgkmcnt(0)" ::: "memory");
; }
; template <int PART>
; __device__ __forceinline__ void prologue(const Params& p, LAS unsigned char* lds, int G, int blk) {
;     ...
;         if (r < I3) { const int kb = r / 64, nb = r % 64; tr_item(p.w_mo, 2048, 2048, kb * 64, nb * 32, Wmo + (size_t)(nb * 32) * 2048, scr, lane); continue; }
.LBB0_177:
	v_lshl_add_u64 v[72:73], v[40:41], 0, s[6:7]
	v_lshl_add_u64 v[74:75], v[38:39], 0, s[6:7]
	v_lshl_add_u64 v[76:77], v[36:37], 0, s[6:7]
	v_lshl_add_u64 v[78:79], v[34:35], 0, s[6:7]
	v_lshl_add_u64 v[80:81], v[32:33], 0, s[6:7]
	v_lshl_add_u64 v[82:83], v[30:31], 0, s[6:7]
	v_lshl_add_u64 v[84:85], v[28:29], 0, s[6:7]
	v_lshl_add_u64 v[86:87], v[26:27], 0, s[6:7]
	global_load_dword v112, v[72:73], off nt
	global_load_dword v113, v[74:75], off nt
	global_load_dword v114, v[76:77], off nt
	global_load_dword v115, v[78:79], off nt
	global_load_dword v116, v[80:81], off nt
	global_load_dword v117, v[82:83], off nt
	global_load_dword v118, v[84:85], off nt
	global_load_dword v119, v[86:87], off nt
	s_add_u32 s6, s6, 0x20000
	s_addc_u32 s7, s7, 0
	v_lshl_add_u64 v[72:73], v[40:41], 0, s[6:7]
	v_lshl_add_u64 v[74:75], v[38:39], 0, s[6:7]
	v_lshl_add_u64 v[76:77], v[36:37], 0, s[6:7]
	v_lshl_add_u64 v[78:79], v[34:35], 0, s[6:7]
	v_lshl_add_u64 v[80:81], v[32:33], 0, s[6:7]
	v_lshl_add_u64 v[82:83], v[30:31], 0, s[6:7]
	v_lshl_add_u64 v[84:85], v[28:29], 0, s[6:7]
	v_lshl_add_u64 v[86:87], v[26:27], 0, s[6:7]
	global_load_dword v120, v[72:73], off nt
	global_load_dword v121, v[74:75], off nt
	global_load_dword v122, v[76:77], off nt
	global_load_dword v123, v[78:79], off nt
	global_load_dword v124, v[80:81], off nt
	global_load_dword v125, v[82:83], off nt
	global_load_dword v126, v[84:85], off nt
	global_load_dword v127, v[86:87], off nt
	s_add_u32 s6, s6, 0x20000
	s_addc_u32 s7, s7, 0
	v_lshl_add_u64 v[72:73], v[40:41], 0, s[6:7]
	v_lshl_add_u64 v[74:75], v[38:39], 0, s[6:7]
	v_lshl_add_u64 v[76:77], v[36:37], 0, s[6:7]
	v_lshl_add_u64 v[78:79], v[34:35], 0, s[6:7]
	v_lshl_add_u64 v[80:81], v[32:33], 0, s[6:7]
	v_lshl_add_u64 v[82:83], v[30:31], 0, s[6:7]
	v_lshl_add_u64 v[84:85], v[28:29], 0, s[6:7]
	v_lshl_add_u64 v[86:87], v[26:27], 0, s[6:7]
	global_load_dword v128, v[72:73], off nt
	global_load_dword v129, v[74:75], off nt
	global_load_dword v130, v[76:77], off nt
	global_load_dword v131, v[78:79], off nt
	global_load_dword v132, v[80:81], off nt
	global_load_dword v133, v[82:83], off nt
	global_load_dword v134, v[84:85], off nt
	global_load_dword v135, v[86:87], off nt
	s_add_u32 s6, s6, 0x20000
	s_addc_u32 s7, s7, 0
	v_lshl_add_u64 v[72:73], v[40:41], 0, s[6:7]
	v_lshl_add_u64 v[74:75], v[38:39], 0, s[6:7]
	v_lshl_add_u64 v[76:77], v[36:37], 0, s[6:7]
	v_lshl_add_u64 v[78:79], v[34:35], 0, s[6:7]
	v_lshl_add_u64 v[80:81], v[32:33], 0, s[6:7]
	v_lshl_add_u64 v[82:83], v[30:31], 0, s[6:7]
	v_lshl_add_u64 v[84:85], v[28:29], 0, s[6:7]
	v_lshl_add_u64 v[86:87], v[26:27], 0, s[6:7]
	global_load_dword v136, v[72:73], off nt
	global_load_dword v137, v[74:75], off nt
	global_load_dword v138, v[76:77], off nt
	global_load_dword v139, v[78:79], off nt
	global_load_dword v140, v[80:81], off nt
	global_load_dword v141, v[82:83], off nt
	global_load_dword v142, v[84:85], off nt
	global_load_dword v143, v[86:87], off nt
	s_add_u32 s6, s6, 0x20000
	s_addc_u32 s7, s7, 0
	v_add_u32_e32 v78, 0x400, v2
	s_waitcnt vmcnt(30)
	ds_write2_b32 v2, v112, v113 offset1:66
	s_waitcnt vmcnt(28)
	ds_write2_b32 v2, v114, v115 offset0:132 offset1:198
	s_waitcnt vmcnt(26)
	ds_write2_b32 v78, v116, v117 offset0:8 offset1:74
	s_waitcnt vmcnt(24)
	ds_write2_b32 v78, v118, v119 offset0:140 offset1:206
	v_add_u32_e32 v2, 0x840, v2
	v_add_u32_e32 v78, 0x400, v2
	s_waitcnt vmcnt(22)
	ds_write2_b32 v2, v120, v121 offset1:66
	s_waitcnt vmcnt(20)
	ds_write2_b32 v2, v122, v123 offset0:132 offset1:198
	s_waitcnt vmcnt(18)
	ds_write2_b32 v78, v124, v125 offset0:8 offset1:74
	s_waitcnt vmcnt(16)
	ds_write2_b32 v78, v126, v127 offset0:140 offset1:206
	v_add_u32_e32 v2, 0x840, v2
	v_add_u32_e32 v78, 0x400, v2
	s_waitcnt vmcnt(14)
	ds_write2_b32 v2, v128, v129 offset1:66
	s_waitcnt vmcnt(12)
	ds_write2_b32 v2, v130, v131 offset0:132 offset1:198
	s_waitcnt vmcnt(10)
	ds_write2_b32 v78, v132, v133 offset0:8 offset1:74
	s_waitcnt vmcnt(8)
	ds_write2_b32 v78, v134, v135 offset0:140 offset1:206
	v_add_u32_e32 v2, 0x840, v2
	v_add_u32_e32 v78, 0x400, v2
	s_waitcnt vmcnt(6)
	ds_write2_b32 v2, v136, v137 offset1:66
	s_waitcnt vmcnt(4)
	ds_write2_b32 v2, v138, v139 offset0:132 offset1:198
	s_waitcnt vmcnt(2)
	ds_write2_b32 v78, v140, v141 offset0:8 offset1:74
	s_waitcnt vmcnt(0)
	ds_write2_b32 v78, v142, v143 offset0:140 offset1:206
	v_add_u32_e32 v2, 0x840, v2
	s_and_b32 s4, s0, 0x3fc0
	s_lshl_b32 s6, s0, 17
	s_addk_i32 s4, 0xd000
	s_and_b32 s6, s6, 0x7e0000
	v_readlane_b32 s7, v245, 6
	s_waitcnt lgkmcnt(0)
	s_add_u32 s14, s7, s6
	v_readlane_b32 s6, v245, 7
	ds_read2_b32 v[30:31], v5 offset0:33 offset1:41
	ds_read2_b32 v[32:33], v5 offset1:8
	ds_read2_b32 v[34:35], v5 offset0:66 offset1:74
	ds_read2_b32 v[36:37], v5 offset0:99 offset1:107
	ds_read2_b32 v[38:39], v5 offset0:132 offset1:140
	ds_read2_b32 v[40:41], v5 offset0:165 offset1:173
	ds_read2_b32 v[72:73], v5 offset0:198 offset1:206
	ds_read2_b32 v[74:75], v5 offset0:231 offset1:239
	s_addc_u32 s15, s6, 0
	s_lshl_b64 s[6:7], s[4:5], 1
	s_add_u32 s6, s14, s6
	s_addc_u32 s7, s15, s7
	v_lshlrev_b32_e32 v2, 1, v0
	v_lshl_add_u64 v[76:77], s[6:7], 0, v[2:3]
	v_lshlrev_b32_e32 v2, 1, v4
	s_waitcnt lgkmcnt(6)
	v_cvt_pk_bf16_f32 v26, v32, v30
	s_waitcnt lgkmcnt(4)
	v_cvt_pk_bf16_f32 v27, v34, v36
	s_waitcnt lgkmcnt(2)
	v_cvt_pk_bf16_f32 v28, v38, v40
	s_waitcnt lgkmcnt(0)
	v_cvt_pk_bf16_f32 v29, v72, v74
	v_lshl_add_u64 v[78:79], v[76:77], 0, v[2:3]
	global_store_dwordx4 v[78:79], v[26:29], off nt
	v_lshlrev_b32_e32 v2, 1, v6
	s_nop 0
	v_cvt_pk_bf16_f32 v26, v33, v31
	v_cvt_pk_bf16_f32 v27, v35, v37
	v_cvt_pk_bf16_f32 v28, v39, v41
	v_cvt_pk_bf16_f32 v29, v73, v75
	ds_read2_b32 v[32:33], v5 offset0:49 offset1:57
	ds_read2_b32 v[34:35], v5 offset0:16 offset1:24
	ds_read2_b32 v[36:37], v5 offset0:82 offset1:90
	ds_read2_b32 v[38:39], v5 offset0:115 offset1:123
	ds_read2_b32 v[40:41], v5 offset0:148 offset1:156
	ds_read2_b32 v[72:73], v5 offset0:181 offset1:189
	ds_read2_b32 v[74:75], v5 offset0:214 offset1:222
	ds_read2_b32 v[78:79], v5 offset0:247 offset1:255
	v_lshl_add_u64 v[30:31], v[76:77], 0, v[2:3]
	v_lshlrev_b32_e32 v2, 1, v8
	global_store_dwordx4 v[30:31], v[26:29], off nt
	v_lshl_add_u64 v[30:31], v[76:77], 0, v[2:3]
	v_lshlrev_b32_e32 v2, 1, v10
	s_waitcnt lgkmcnt(6)
	v_cvt_pk_bf16_f32 v26, v34, v32
	s_waitcnt lgkmcnt(4)
	v_cvt_pk_bf16_f32 v27, v36, v38
	s_waitcnt lgkmcnt(2)
	v_cvt_pk_bf16_f32 v28, v40, v72
	s_waitcnt lgkmcnt(0)
	v_cvt_pk_bf16_f32 v29, v74, v78
	global_store_dwordx4 v[30:31], v[26:29], off nt
	v_lshl_add_u64 v[30:31], v[76:77], 0, v[2:3]
	s_nop 0
	v_cvt_pk_bf16_f32 v26, v35, v33
	v_cvt_pk_bf16_f32 v27, v37, v39
	v_cvt_pk_bf16_f32 v28, v41, v73
	v_cvt_pk_bf16_f32 v29, v75, v79
	global_store_dwordx4 v[30:31], v[26:29], off nt
	s_waitcnt lgkmcnt(0)

; #define LAS __attribute__((address_space(3)))
; __device__ __forceinline__ unsigned cvtpk(float lo, float hi) { f32x2_t v = {lo, hi}; bf16x2_t b = __builtin_convertvector(v, bf16x2_t); return __builtin_bit_cast(unsigned, b); }
; #define NTL(p) __builtin_nontemporal_load(&(p))
; __device__ __forceinline__ void tr_item(const float* W, int N, int K, int k0, int n0, bf16_t* dst, LAS float* scr, int lane) {
; #pragma unroll 8
;     for (int i = 0; i < 32; ++i) { const int kk = 2 * i + (lane >> 5); scr[kk * 33 + (lane & 31)] = NTL(W[(size_t)(k0 + kk) * N + n0 + (lane & 31)]); }
;     asm volatile("s_waitcnt lgkmcnt(0)" ::: "memory");
;     const int c = lane & 7;
; #pragma unroll
;     for (int j = 0; j < 4; ++j) { const int n = (lane >> 3) + 8 * j; const LAS float* s = scr + (8 * c) * 33 + n;
;         u32x4 o; o.x = cvtpk(s[0 * 33], s[1 * 33]); o.y = cvtpk(s[2 * 33], s[3 * 33]); o.z = cvtpk(s[4 * 33], s[5 * 33]); o.w = cvtpk(s[6 * 33], s[7 * 33]);
;         *(u32x4*)(dst + (size_t)n * K + k0 + 8 * c) = o; }
;     asm volatile("s_waitcnt lgkmcnt(0)" ::: "memory");
; }
; template <int PART>
; __device__ __forceinline__ void prologue(const Params& p, LAS unsigned char* lds, int G, int blk) {
;     ...
;         if (r < I2) { const int kb = r / 128, nb = r % 128; tr_item(p.w_mkv, 4096, 2048, kb * 64, nb * 32, Wmkv + (size_t)(nb * 32) * 2048, scr, lane); continue; }
.LBB0_182:
	v_lshl_add_u64 v[72:73], v[40:41], 0, s[6:7]
	v_lshl_add_u64 v[74:75], v[38:39], 0, s[6:7]
	v_lshl_add_u64 v[76:77], v[36:37], 0, s[6:7]
	v_lshl_add_u64 v[78:79], v[34:35], 0, s[6:7]
	v_lshl_add_u64 v[80:81], v[32:33], 0, s[6:7]
	v_lshl_add_u64 v[82:83], v[30:31], 0, s[6:7]
	v_lshl_add_u64 v[84:85], v[28:29], 0, s[6:7]
	v_lshl_add_u64 v[86:87], v[26:27], 0, s[6:7]
	global_load_dword v112, v[72:73], off nt
	global_load_dword v113, v[74:75], off nt
	global_load_dword v114, v[76:77], off nt
	global_load_dword v115, v[78:79], off nt
	global_load_dword v116, v[80:81], off nt
	global_load_dword v117, v[82:83], off nt
	global_load_dword v118, v[84:85], off nt
	global_load_dword v119, v[86:87], off nt
	s_add_u32 s6, s6, 0x40000
	s_addc_u32 s7, s7, 0
	v_lshl_add_u64 v[72:73], v[40:41], 0, s[6:7]
	v_lshl_add_u64 v[74:75], v[38:39], 0, s[6:7]
	v_lshl_add_u64 v[76:77], v[36:37], 0, s[6:7]
	v_lshl_add_u64 v[78:79], v[34:35], 0, s[6:7]
	v_lshl_add_u64 v[80:81], v[32:33], 0, s[6:7]
	v_lshl_add_u64 v[82:83], v[30:31], 0, s[6:7]
	v_lshl_add_u64 v[84:85], v[28:29], 0, s[6:7]
	v_lshl_add_u64 v[86:87], v[26:27], 0, s[6:7]
	global_load_dword v120, v[72:73], off nt
	global_load_dword v121, v[74:75], off nt
	global_load_dword v122, v[76:77], off nt
	global_load_dword v123, v[78:79], off nt
	global_load_dword v124, v[80:81], off nt
	global_load_dword v125, v[82:83], off nt
	global_load_dword v126, v[84:85], off nt
	global_load_dword v127, v[86:87], off nt
	s_add_u32 s6, s6, 0x40000
	s_addc_u32 s7, s7, 0
	v_lshl_add_u64 v[72:73], v[40:41], 0, s[6:7]
	v_lshl_add_u64 v[74:75], v[38:39], 0, s[6:7]
	v_lshl_add_u64 v[76:77], v[36:37], 0, s[6:7]
	v_lshl_add_u64 v[78:79], v[34:35], 0, s[6:7]
	v_lshl_add_u64 v[80:81], v[32:33], 0, s[6:7]
	v_lshl_add_u64 v[82:83], v[30:31], 0, s[6:7]
	v_lshl_add_u64 v[84:85], v[28:29], 0, s[6:7]
	v_lshl_add_u64 v[86:87], v[26:27], 0, s[6:7]
	global_load_dword v128, v[72:73], off nt
	global_load_dword v129, v[74:75], off nt
	global_load_dword v130, v[76:77], off nt
	global_load_dword v131, v[78:79], off nt
	global_load_dword v132, v[80:81], off nt
	global_load_dword v133, v[82:83], off nt
	global_load_dword v134, v[84:85], off nt
	global_load_dword v135, v[86:87], off nt
	s_add_u32 s6, s6, 0x40000
	s_addc_u32 s7, s7, 0
	v_lshl_add_u64 v[72:73], v[40:41], 0, s[6:7]
	v_lshl_add_u64 v[74:75], v[38:39], 0, s[6:7]
	v_lshl_add_u64 v[76:77], v[36:37], 0, s[6:7]
	v_lshl_add_u64 v[78:79], v[34:35], 0, s[6:7]
	v_lshl_add_u64 v[80:81], v[32:33], 0, s[6:7]
	v_lshl_add_u64 v[82:83], v[30:31], 0, s[6:7]
	v_lshl_add_u64 v[84:85], v[28:29], 0, s[6:7]
	v_lshl_add_u64 v[86:87], v[26:27], 0, s[6:7]
	global_load_dword v136, v[72:73], off nt
	global_load_dword v137, v[74:75], off nt
	global_load_dword v138, v[76:77], off nt
	global_load_dword v139, v[78:79], off nt
	global_load_dword v140, v[80:81], off nt
	global_load_dword v141, v[82:83], off nt
	global_load_dword v142, v[84:85], off nt
	global_load_dword v143, v[86:87], off nt
	s_add_u32 s6, s6, 0x40000
	s_addc_u32 s7, s7, 0
	v_add_u32_e32 v78, 0x400, v2
	s_waitcnt vmcnt(30)
	ds_write2_b32 v2, v112, v113 offset1:66
	s_waitcnt vmcnt(28)
	ds_write2_b32 v2, v114, v115 offset0:132 offset1:198
	s_waitcnt vmcnt(26)
	ds_write2_b32 v78, v116, v117 offset0:8 offset1:74
	s_waitcnt vmcnt(24)
	ds_write2_b32 v78, v118, v119 offset0:140 offset1:206
	v_add_u32_e32 v2, 0x840, v2
	v_add_u32_e32 v78, 0x400, v2
	s_waitcnt vmcnt(22)
	ds_write2_b32 v2, v120, v121 offset1:66
	s_waitcnt vmcnt(20)
	ds_write2_b32 v2, v122, v123 offset0:132 offset1:198
	s_waitcnt vmcnt(18)
	ds_write2_b32 v78, v124, v125 offset0:8 offset1:74
	s_waitcnt vmcnt(16)
	ds_write2_b32 v78, v126, v127 offset0:140 offset1:206
	v_add_u32_e32 v2, 0x840, v2
	v_add_u32_e32 v78, 0x400, v2
	s_waitcnt vmcnt(14)
	ds_write2_b32 v2, v128, v129 offset1:66
	s_waitcnt vmcnt(12)
	ds_write2_b32 v2, v130, v131 offset0:132 offset1:198
	s_waitcnt vmcnt(10)
	ds_write2_b32 v78, v132, v133 offset0:8 offset1:74
	s_waitcnt vmcnt(8)
	ds_write2_b32 v78, v134, v135 offset0:140 offset1:206
	v_add_u32_e32 v2, 0x840, v2
	v_add_u32_e32 v78, 0x400, v2
	s_waitcnt vmcnt(6)
	ds_write2_b32 v2, v136, v137 offset1:66
	s_waitcnt vmcnt(4)
	ds_write2_b32 v2, v138, v139 offset0:132 offset1:198
	s_waitcnt vmcnt(2)
	ds_write2_b32 v78, v140, v141 offset0:8 offset1:74
	s_waitcnt vmcnt(0)
	ds_write2_b32 v78, v142, v143 offset0:140 offset1:206
	v_add_u32_e32 v2, 0x840, v2
	s_lshl_b32 s6, s0, 17
	s_add_i32 s4, s0, 0xffffe000
	s_and_b32 s6, s6, 0xfe0000
	v_readlane_b32 s7, v245, 4
	s_waitcnt lgkmcnt(0)
	s_add_u32 s6, s7, s6
	v_readlane_b32 s7, v245, 5
	ds_read2_b32 v[30:31], v5 offset0:33 offset1:41
	ds_read2_b32 v[32:33], v5 offset1:8
	ds_read2_b32 v[34:35], v5 offset0:66 offset1:74
	ds_read2_b32 v[36:37], v5 offset0:99 offset1:107
	ds_read2_b32 v[38:39], v5 offset0:132 offset1:140
	ds_read2_b32 v[40:41], v5 offset0:165 offset1:173
	ds_read2_b32 v[72:73], v5 offset0:198 offset1:206
	ds_read2_b32 v[74:75], v5 offset0:231 offset1:239
	s_addc_u32 s7, s7, 0
	s_and_b32 s4, s4, 0xffffff80
	s_add_u32 s6, s6, s4
	s_addc_u32 s7, s7, 0
	v_lshlrev_b32_e32 v2, 1, v0
	v_lshl_add_u64 v[76:77], s[6:7], 0, v[2:3]
	v_lshlrev_b32_e32 v2, 1, v4
	s_waitcnt lgkmcnt(6)
	v_cvt_pk_bf16_f32 v26, v32, v30
	s_waitcnt lgkmcnt(4)
	v_cvt_pk_bf16_f32 v27, v34, v36
	s_waitcnt lgkmcnt(2)
	v_cvt_pk_bf16_f32 v28, v38, v40
	s_waitcnt lgkmcnt(0)
	v_cvt_pk_bf16_f32 v29, v72, v74
	v_lshl_add_u64 v[78:79], v[76:77], 0, v[2:3]
	global_store_dwordx4 v[78:79], v[26:29], off nt
	v_lshlrev_b32_e32 v2, 1, v6
	s_nop 0
	v_cvt_pk_bf16_f32 v26, v33, v31
	v_cvt_pk_bf16_f32 v27, v35, v37
	v_cvt_pk_bf16_f32 v28, v39, v41
	v_cvt_pk_bf16_f32 v29, v73, v75
	ds_read2_b32 v[32:33], v5 offset0:49 offset1:57
	ds_read2_b32 v[34:35], v5 offset0:16 offset1:24
	ds_read2_b32 v[36:37], v5 offset0:82 offset1:90
	ds_read2_b32 v[38:39], v5 offset0:115 offset1:123
	ds_read2_b32 v[40:41], v5 offset0:148 offset1:156
	ds_read2_b32 v[72:73], v5 offset0:181 offset1:189
	ds_read2_b32 v[74:75], v5 offset0:214 offset1:222
	ds_read2_b32 v[78:79], v5 offset0:247 offset1:255
	v_lshl_add_u64 v[30:31], v[76:77], 0, v[2:3]
	v_lshlrev_b32_e32 v2, 1, v8
	global_store_dwordx4 v[30:31], v[26:29], off nt
	v_lshl_add_u64 v[30:31], v[76:77], 0, v[2:3]
	v_lshlrev_b32_e32 v2, 1, v10
	s_waitcnt lgkmcnt(6)
	v_cvt_pk_bf16_f32 v26, v34, v32
	s_waitcnt lgkmcnt(4)
	v_cvt_pk_bf16_f32 v27, v36, v38
	s_waitcnt lgkmcnt(2)
	v_cvt_pk_bf16_f32 v28, v40, v72
	s_waitcnt lgkmcnt(0)
	v_cvt_pk_bf16_f32 v29, v74, v78
	global_store_dwordx4 v[30:31], v[26:29], off nt
	v_lshl_add_u64 v[30:31], v[76:77], 0, v[2:3]
	s_nop 0
	v_cvt_pk_bf16_f32 v26, v35, v33
	v_cvt_pk_bf16_f32 v27, v37, v39
	v_cvt_pk_bf16_f32 v28, v41, v73
	v_cvt_pk_bf16_f32 v29, v75, v79
	global_store_dwordx4 v[30:31], v[26:29], off nt
	s_waitcnt lgkmcnt(0)

; #define LAS __attribute__((address_space(3)))
; __device__ __forceinline__ unsigned cvtpk(float lo, float hi) { f32x2_t v = {lo, hi}; bf16x2_t b = __builtin_convertvector(v, bf16x2_t); return __builtin_bit_cast(unsigned, b); }
; #define NTL(p) __builtin_nontemporal_load(&(p))
; __device__ __forceinline__ void tr_item(const float* W, int N, int K, int k0, int n0, bf16_t* dst, LAS float* scr, int lane) {
; #pragma unroll 8
;     for (int i = 0; i < 32; ++i) { const int kk = 2 * i + (lane >> 5); scr[kk * 33 + (lane & 31)] = NTL(W[(size_t)(k0 + kk) * N + n0 + (lane & 31)]); }
;     asm volatile("s_waitcnt lgkmcnt(0)" ::: "memory");
;     const int c = lane & 7;
; #pragma unroll
;     for (int j = 0; j < 4; ++j) { const int n = (lane >> 3) + 8 * j; const LAS float* s = scr + (8 * c) * 33 + n;
;         u32x4 o; o.x = cvtpk(s[0 * 33], s[1 * 33]); o.y = cvtpk(s[2 * 33], s[3 * 33]); o.z = cvtpk(s[4 * 33], s[5 * 33]); o.w = cvtpk(s[6 * 33], s[7 * 33]);
;         *(u32x4*)(dst + (size_t)n * K + k0 + 8 * c) = o; }
;     asm volatile("s_waitcnt lgkmcnt(0)" ::: "memory");
; }
; template <int PART>
; __device__ __forceinline__ void prologue(const Params& p, LAS unsigned char* lds, int G, int blk) {
;     ...
;         if (r < I1) { const int kb = r / 64, nb = r % 64; tr_item(p.w_out, 2048, 2048, kb * 64, nb * 32, Wout + (size_t)(nb * 32) * 2048, scr, lane); continue; }
.LBB0_187:
	v_lshl_add_u64 v[72:73], v[40:41], 0, s[6:7]
	v_lshl_add_u64 v[74:75], v[38:39], 0, s[6:7]
	v_lshl_add_u64 v[76:77], v[36:37], 0, s[6:7]
	v_lshl_add_u64 v[78:79], v[34:35], 0, s[6:7]
	v_lshl_add_u64 v[80:81], v[32:33], 0, s[6:7]
	v_lshl_add_u64 v[82:83], v[30:31], 0, s[6:7]
	v_lshl_add_u64 v[84:85], v[28:29], 0, s[6:7]
	v_lshl_add_u64 v[86:87], v[26:27], 0, s[6:7]
	global_load_dword v112, v[72:73], off nt
	global_load_dword v113, v[74:75], off nt
	global_load_dword v114, v[76:77], off nt
	global_load_dword v115, v[78:79], off nt
	global_load_dword v116, v[80:81], off nt
	global_load_dword v117, v[82:83], off nt
	global_load_dword v118, v[84:85], off nt
	global_load_dword v119, v[86:87], off nt
	s_add_u32 s6, s6, 0x20000
	s_addc_u32 s7, s7, 0
	v_lshl_add_u64 v[72:73], v[40:41], 0, s[6:7]
	v_lshl_add_u64 v[74:75], v[38:39], 0, s[6:7]
	v_lshl_add_u64 v[76:77], v[36:37], 0, s[6:7]
	v_lshl_add_u64 v[78:79], v[34:35], 0, s[6:7]
	v_lshl_add_u64 v[80:81], v[32:33], 0, s[6:7]
	v_lshl_add_u64 v[82:83], v[30:31], 0, s[6:7]
	v_lshl_add_u64 v[84:85], v[28:29], 0, s[6:7]
	v_lshl_add_u64 v[86:87], v[26:27], 0, s[6:7]
	global_load_dword v120, v[72:73], off nt
	global_load_dword v121, v[74:75], off nt
	global_load_dword v122, v[76:77], off nt
	global_load_dword v123, v[78:79], off nt
	global_load_dword v124, v[80:81], off nt
	global_load_dword v125, v[82:83], off nt
	global_load_dword v126, v[84:85], off nt
	global_load_dword v127, v[86:87], off nt
	s_add_u32 s6, s6, 0x20000
	s_addc_u32 s7, s7, 0
	v_lshl_add_u64 v[72:73], v[40:41], 0, s[6:7]
	v_lshl_add_u64 v[74:75], v[38:39], 0, s[6:7]
	v_lshl_add_u64 v[76:77], v[36:37], 0, s[6:7]
	v_lshl_add_u64 v[78:79], v[34:35], 0, s[6:7]
	v_lshl_add_u64 v[80:81], v[32:33], 0, s[6:7]
	v_lshl_add_u64 v[82:83], v[30:31], 0, s[6:7]
	v_lshl_add_u64 v[84:85], v[28:29], 0, s[6:7]
	v_lshl_add_u64 v[86:87], v[26:27], 0, s[6:7]
	global_load_dword v128, v[72:73], off nt
	global_load_dword v129, v[74:75], off nt
	global_load_dword v130, v[76:77], off nt
	global_load_dword v131, v[78:79], off nt
	global_load_dword v132, v[80:81], off nt
	global_load_dword v133, v[82:83], off nt
	global_load_dword v134, v[84:85], off nt
	global_load_dword v135, v[86:87], off nt
	s_add_u32 s6, s6, 0x20000
	s_addc_u32 s7, s7, 0
	v_lshl_add_u64 v[72:73], v[40:41], 0, s[6:7]
	v_lshl_add_u64 v[74:75], v[38:39], 0, s[6:7]
	v_lshl_add_u64 v[76:77], v[36:37], 0, s[6:7]
	v_lshl_add_u64 v[78:79], v[34:35], 0, s[6:7]
	v_lshl_add_u64 v[80:81], v[32:33], 0, s[6:7]
	v_lshl_add_u64 v[82:83], v[30:31], 0, s[6:7]
	v_lshl_add_u64 v[84:85], v[28:29], 0, s[6:7]
	v_lshl_add_u64 v[86:87], v[26:27], 0, s[6:7]
	global_load_dword v136, v[72:73], off nt
	global_load_dword v137, v[74:75], off nt
	global_load_dword v138, v[76:77], off nt
	global_load_dword v139, v[78:79], off nt
	global_load_dword v140, v[80:81], off nt
	global_load_dword v141, v[82:83], off nt
	global_load_dword v142, v[84:85], off nt
	global_load_dword v143, v[86:87], off nt
	s_add_u32 s6, s6, 0x20000
	s_addc_u32 s7, s7, 0
	v_add_u32_e32 v78, 0x400, v2
	s_waitcnt vmcnt(30)
	ds_write2_b32 v2, v112, v113 offset1:66
	s_waitcnt vmcnt(28)
	ds_write2_b32 v2, v114, v115 offset0:132 offset1:198
	s_waitcnt vmcnt(26)
	ds_write2_b32 v78, v116, v117 offset0:8 offset1:74
	s_waitcnt vmcnt(24)
	ds_write2_b32 v78, v118, v119 offset0:140 offset1:206
	v_add_u32_e32 v2, 0x840, v2
	v_add_u32_e32 v78, 0x400, v2
	s_waitcnt vmcnt(22)
	ds_write2_b32 v2, v120, v121 offset1:66
	s_waitcnt vmcnt(20)
	ds_write2_b32 v2, v122, v123 offset0:132 offset1:198
	s_waitcnt vmcnt(18)
	ds_write2_b32 v78, v124, v125 offset0:8 offset1:74
	s_waitcnt vmcnt(16)
	ds_write2_b32 v78, v126, v127 offset0:140 offset1:206
	v_add_u32_e32 v2, 0x840, v2
	v_add_u32_e32 v78, 0x400, v2
	s_waitcnt vmcnt(14)
	ds_write2_b32 v2, v128, v129 offset1:66
	s_waitcnt vmcnt(12)
	ds_write2_b32 v2, v130, v131 offset0:132 offset1:198
	s_waitcnt vmcnt(10)
	ds_write2_b32 v78, v132, v133 offset0:8 offset1:74
	s_waitcnt vmcnt(8)
	ds_write2_b32 v78, v134, v135 offset0:140 offset1:206
	v_add_u32_e32 v2, 0x840, v2
	v_add_u32_e32 v78, 0x400, v2
	s_waitcnt vmcnt(6)
	ds_write2_b32 v2, v136, v137 offset1:66
	s_waitcnt vmcnt(4)
	ds_write2_b32 v2, v138, v139 offset0:132 offset1:198
	s_waitcnt vmcnt(2)
	ds_write2_b32 v78, v140, v141 offset0:8 offset1:74
	s_waitcnt vmcnt(0)
	ds_write2_b32 v78, v142, v143 offset0:140 offset1:206
	v_add_u32_e32 v2, 0x840, v2
	s_and_b32 s4, s0, 0x1fc0
	s_lshl_b32 s6, s0, 17
	s_addk_i32 s4, 0xe800
	s_and_b32 s6, s6, 0x7e0000
	s_waitcnt lgkmcnt(0)
	s_add_u32 s14, s58, s6
	ds_read2_b32 v[30:31], v5 offset0:33 offset1:41
	ds_read2_b32 v[32:33], v5 offset1:8
	ds_read2_b32 v[34:35], v5 offset0:66 offset1:74
	ds_read2_b32 v[36:37], v5 offset0:99 offset1:107
	ds_read2_b32 v[38:39], v5 offset0:132 offset1:140
	ds_read2_b32 v[40:41], v5 offset0:165 offset1:173
	ds_read2_b32 v[72:73], v5 offset0:198 offset1:206
	ds_read2_b32 v[74:75], v5 offset0:231 offset1:239
	s_addc_u32 s15, s59, 0
	s_lshl_b64 s[6:7], s[4:5], 1
	s_add_u32 s6, s14, s6
	s_addc_u32 s7, s15, s7
	v_lshlrev_b32_e32 v2, 1, v0
	v_lshl_add_u64 v[76:77], s[6:7], 0, v[2:3]
	v_lshlrev_b32_e32 v2, 1, v4
	s_waitcnt lgkmcnt(6)
	v_cvt_pk_bf16_f32 v26, v32, v30
	s_waitcnt lgkmcnt(4)
	v_cvt_pk_bf16_f32 v27, v34, v36
	s_waitcnt lgkmcnt(2)
	v_cvt_pk_bf16_f32 v28, v38, v40
	s_waitcnt lgkmcnt(0)
	v_cvt_pk_bf16_f32 v29, v72, v74
	v_lshl_add_u64 v[78:79], v[76:77], 0, v[2:3]
	global_store_dwordx4 v[78:79], v[26:29], off nt
	v_lshlrev_b32_e32 v2, 1, v6
	s_nop 0
	v_cvt_pk_bf16_f32 v26, v33, v31
	v_cvt_pk_bf16_f32 v27, v35, v37
	v_cvt_pk_bf16_f32 v28, v39, v41
	v_cvt_pk_bf16_f32 v29, v73, v75
	ds_read2_b32 v[32:33], v5 offset0:49 offset1:57
	ds_read2_b32 v[34:35], v5 offset0:16 offset1:24
	ds_read2_b32 v[36:37], v5 offset0:82 offset1:90
	ds_read2_b32 v[38:39], v5 offset0:115 offset1:123
	ds_read2_b32 v[40:41], v5 offset0:148 offset1:156
	ds_read2_b32 v[72:73], v5 offset0:181 offset1:189
	ds_read2_b32 v[74:75], v5 offset0:214 offset1:222
	ds_read2_b32 v[78:79], v5 offset0:247 offset1:255
	v_lshl_add_u64 v[30:31], v[76:77], 0, v[2:3]
	v_lshlrev_b32_e32 v2, 1, v8
	global_store_dwordx4 v[30:31], v[26:29], off nt
	v_lshl_add_u64 v[30:31], v[76:77], 0, v[2:3]
	v_lshlrev_b32_e32 v2, 1, v10
	s_waitcnt lgkmcnt(6)
	v_cvt_pk_bf16_f32 v26, v34, v32
	s_waitcnt lgkmcnt(4)
	v_cvt_pk_bf16_f32 v27, v36, v38
	s_waitcnt lgkmcnt(2)
	v_cvt_pk_bf16_f32 v28, v40, v72
	s_waitcnt lgkmcnt(0)
	v_cvt_pk_bf16_f32 v29, v74, v78
	global_store_dwordx4 v[30:31], v[26:29], off nt
	v_lshl_add_u64 v[30:31], v[76:77], 0, v[2:3]
	s_nop 0
	v_cvt_pk_bf16_f32 v26, v35, v33
	v_cvt_pk_bf16_f32 v27, v37, v39
	v_cvt_pk_bf16_f32 v28, v41, v73
	v_cvt_pk_bf16_f32 v29, v75, v79
	global_store_dwordx4 v[30:31], v[26:29], off nt
	s_waitcnt lgkmcnt(0)

; #define LAS __attribute__((address_space(3)))
; __device__ __forceinline__ unsigned cvtpk(float lo, float hi) { f32x2_t v = {lo, hi}; bf16x2_t b = __builtin_convertvector(v, bf16x2_t); return __builtin_bit_cast(unsigned, b); }
; #define NTL(p) __builtin_nontemporal_load(&(p))
; __device__ __forceinline__ void tr_item(const float* W, int N, int K, int k0, int n0, bf16_t* dst, LAS float* scr, int lane) {
; #pragma unroll 8
;     for (int i = 0; i < 32; ++i) { const int kk = 2 * i + (lane >> 5); scr[kk * 33 + (lane & 31)] = NTL(W[(size_t)(k0 + kk) * N + n0 + (lane & 31)]); }
;     asm volatile("s_waitcnt lgkmcnt(0)" ::: "memory");
;     const int c = lane & 7;
; #pragma unroll
;     for (int j = 0; j < 4; ++j) { const int n = (lane >> 3) + 8 * j; const LAS float* s = scr + (8 * c) * 33 + n;
;         u32x4 o; o.x = cvtpk(s[0 * 33], s[1 * 33]); o.y = cvtpk(s[2 * 33], s[3 * 33]); o.z = cvtpk(s[4 * 33], s[5 * 33]); o.w = cvtpk(s[6 * 33], s[7 * 33]);
;         *(u32x4*)(dst + (size_t)n * K + k0 + 8 * c) = o; }
;     asm volatile("s_waitcnt lgkmcnt(0)" ::: "memory");
; }
; template <int PART>
; __device__ __forceinline__ void prologue(const Params& p, LAS unsigned char* lds, int G, int blk) {
;     ...
;         if (r < I0) { const int kb = r / 192, nb = r % 192, n0 = nb * 32; bf16_t* dst;
;             if (n0 < 2048) dst = Wqk + (size_t)n0 * 2048;
;             else if (n0 < 3072) dst = Wv + (size_t)(n0 - 2048) * 2048;
;             else if (n0 < 5120) dst = Wqk + (size_t)(2048 + n0 - 3072) * 2048;
;             else dst = Wv + (size_t)(1024 + n0 - 5120) * 2048;
;             tr_item(p.w_in, 6144, 2048, kb * 64, n0, dst, scr, lane); continue; }
.LBB0_204:
	v_lshl_add_u64 v[72:73], v[40:41], 0, s[20:21]
	v_lshl_add_u64 v[74:75], v[38:39], 0, s[20:21]
	v_lshl_add_u64 v[76:77], v[36:37], 0, s[20:21]
	v_lshl_add_u64 v[78:79], v[34:35], 0, s[20:21]
	v_lshl_add_u64 v[80:81], v[32:33], 0, s[20:21]
	v_lshl_add_u64 v[82:83], v[30:31], 0, s[20:21]
	v_lshl_add_u64 v[84:85], v[28:29], 0, s[20:21]
	v_lshl_add_u64 v[86:87], v[26:27], 0, s[20:21]
	global_load_dword v112, v[72:73], off nt
	global_load_dword v113, v[74:75], off nt
	global_load_dword v114, v[76:77], off nt
	global_load_dword v115, v[78:79], off nt
	global_load_dword v116, v[80:81], off nt
	global_load_dword v117, v[82:83], off nt
	global_load_dword v118, v[84:85], off nt
	global_load_dword v119, v[86:87], off nt
	s_add_u32 s20, s20, 0x60000
	s_addc_u32 s21, s21, 0
	v_lshl_add_u64 v[72:73], v[40:41], 0, s[20:21]
	v_lshl_add_u64 v[74:75], v[38:39], 0, s[20:21]
	v_lshl_add_u64 v[76:77], v[36:37], 0, s[20:21]
	v_lshl_add_u64 v[78:79], v[34:35], 0, s[20:21]
	v_lshl_add_u64 v[80:81], v[32:33], 0, s[20:21]
	v_lshl_add_u64 v[82:83], v[30:31], 0, s[20:21]
	v_lshl_add_u64 v[84:85], v[28:29], 0, s[20:21]
	v_lshl_add_u64 v[86:87], v[26:27], 0, s[20:21]
	global_load_dword v120, v[72:73], off nt
	global_load_dword v121, v[74:75], off nt
	global_load_dword v122, v[76:77], off nt
	global_load_dword v123, v[78:79], off nt
	global_load_dword v124, v[80:81], off nt
	global_load_dword v125, v[82:83], off nt
	global_load_dword v126, v[84:85], off nt
	global_load_dword v127, v[86:87], off nt
	s_add_u32 s20, s20, 0x60000
	s_addc_u32 s21, s21, 0
	v_lshl_add_u64 v[72:73], v[40:41], 0, s[20:21]
	v_lshl_add_u64 v[74:75], v[38:39], 0, s[20:21]
	v_lshl_add_u64 v[76:77], v[36:37], 0, s[20:21]
	v_lshl_add_u64 v[78:79], v[34:35], 0, s[20:21]
	v_lshl_add_u64 v[80:81], v[32:33], 0, s[20:21]
	v_lshl_add_u64 v[82:83], v[30:31], 0, s[20:21]
	v_lshl_add_u64 v[84:85], v[28:29], 0, s[20:21]
	v_lshl_add_u64 v[86:87], v[26:27], 0, s[20:21]
	global_load_dword v128, v[72:73], off nt
	global_load_dword v129, v[74:75], off nt
	global_load_dword v130, v[76:77], off nt
	global_load_dword v131, v[78:79], off nt
	global_load_dword v132, v[80:81], off nt
	global_load_dword v133, v[82:83], off nt
	global_load_dword v134, v[84:85], off nt
	global_load_dword v135, v[86:87], off nt
	s_add_u32 s20, s20, 0x60000
	s_addc_u32 s21, s21, 0
	v_lshl_add_u64 v[72:73], v[40:41], 0, s[20:21]
	v_lshl_add_u64 v[74:75], v[38:39], 0, s[20:21]
	v_lshl_add_u64 v[76:77], v[36:37], 0, s[20:21]
	v_lshl_add_u64 v[78:79], v[34:35], 0, s[20:21]
	v_lshl_add_u64 v[80:81], v[32:33], 0, s[20:21]
	v_lshl_add_u64 v[82:83], v[30:31], 0, s[20:21]
	v_lshl_add_u64 v[84:85], v[28:29], 0, s[20:21]
	v_lshl_add_u64 v[86:87], v[26:27], 0, s[20:21]
	global_load_dword v136, v[72:73], off nt
	global_load_dword v137, v[74:75], off nt
	global_load_dword v138, v[76:77], off nt
	global_load_dword v139, v[78:79], off nt
	global_load_dword v140, v[80:81], off nt
	global_load_dword v141, v[82:83], off nt
	global_load_dword v142, v[84:85], off nt
	global_load_dword v143, v[86:87], off nt
	s_add_u32 s20, s20, 0x60000
	s_addc_u32 s21, s21, 0
	v_add_u32_e32 v78, 0x400, v2
	s_waitcnt vmcnt(30)
	ds_write2_b32 v2, v112, v113 offset1:66
	s_waitcnt vmcnt(28)
	ds_write2_b32 v2, v114, v115 offset0:132 offset1:198
	s_waitcnt vmcnt(26)
	ds_write2_b32 v78, v116, v117 offset0:8 offset1:74
	s_waitcnt vmcnt(24)
	ds_write2_b32 v78, v118, v119 offset0:140 offset1:206
	v_add_u32_e32 v2, 0x840, v2
	v_add_u32_e32 v78, 0x400, v2
	s_waitcnt vmcnt(22)
	ds_write2_b32 v2, v120, v121 offset1:66
	s_waitcnt vmcnt(20)
	ds_write2_b32 v2, v122, v123 offset0:132 offset1:198
	s_waitcnt vmcnt(18)
	ds_write2_b32 v78, v124, v125 offset0:8 offset1:74
	s_waitcnt vmcnt(16)
	ds_write2_b32 v78, v126, v127 offset0:140 offset1:206
	v_add_u32_e32 v2, 0x840, v2
	v_add_u32_e32 v78, 0x400, v2
	s_waitcnt vmcnt(14)
	ds_write2_b32 v2, v128, v129 offset1:66
	s_waitcnt vmcnt(12)
	ds_write2_b32 v2, v130, v131 offset0:132 offset1:198
	s_waitcnt vmcnt(10)
	ds_write2_b32 v78, v132, v133 offset0:8 offset1:74
	s_waitcnt vmcnt(8)
	ds_write2_b32 v78, v134, v135 offset0:140 offset1:206
	v_add_u32_e32 v2, 0x840, v2
	v_add_u32_e32 v78, 0x400, v2
	s_waitcnt vmcnt(6)
	ds_write2_b32 v2, v136, v137 offset1:66
	s_waitcnt vmcnt(4)
	ds_write2_b32 v2, v138, v139 offset0:132 offset1:198
	s_waitcnt vmcnt(2)
	ds_write2_b32 v78, v140, v141 offset0:8 offset1:74
	s_waitcnt vmcnt(0)
	ds_write2_b32 v78, v142, v143 offset0:140 offset1:206
	v_add_u32_e32 v2, 0x840, v2
	s_lshl_b64 s[6:7], s[6:7], 12
	s_add_u32 s4, s18, s6
	s_waitcnt lgkmcnt(0)
	s_addc_u32 s14, s19, s7
	s_ashr_i32 s39, s38, 31
	ds_read2_b32 v[30:31], v5 offset0:33 offset1:41
	ds_read2_b32 v[32:33], v5 offset1:8
	ds_read2_b32 v[34:35], v5 offset0:66 offset1:74
	ds_read2_b32 v[36:37], v5 offset0:99 offset1:107
	ds_read2_b32 v[38:39], v5 offset0:132 offset1:140
	ds_read2_b32 v[40:41], v5 offset0:165 offset1:173
	ds_read2_b32 v[72:73], v5 offset0:198 offset1:206
	ds_read2_b32 v[74:75], v5 offset0:231 offset1:239
	s_lshl_b64 s[6:7], s[38:39], 1
	s_add_u32 s6, s4, s6
	s_addc_u32 s7, s14, s7
	v_lshlrev_b32_e32 v2, 1, v0
	v_lshl_add_u64 v[76:77], s[6:7], 0, v[2:3]
	v_lshlrev_b32_e32 v2, 1, v4
	s_waitcnt lgkmcnt(6)
	v_cvt_pk_bf16_f32 v26, v32, v30
	s_waitcnt lgkmcnt(4)
	v_cvt_pk_bf16_f32 v27, v34, v36
	s_waitcnt lgkmcnt(2)
	v_cvt_pk_bf16_f32 v28, v38, v40
	s_waitcnt lgkmcnt(0)
	v_cvt_pk_bf16_f32 v29, v72, v74
	v_lshl_add_u64 v[78:79], v[76:77], 0, v[2:3]
	global_store_dwordx4 v[78:79], v[26:29], off nt
	v_lshlrev_b32_e32 v2, 1, v6
	s_nop 0
	v_cvt_pk_bf16_f32 v26, v33, v31
	v_cvt_pk_bf16_f32 v27, v35, v37
	v_cvt_pk_bf16_f32 v28, v39, v41
	v_cvt_pk_bf16_f32 v29, v73, v75
	ds_read2_b32 v[32:33], v5 offset0:49 offset1:57
	ds_read2_b32 v[34:35], v5 offset0:16 offset1:24
	ds_read2_b32 v[36:37], v5 offset0:82 offset1:90
	ds_read2_b32 v[38:39], v5 offset0:115 offset1:123
	ds_read2_b32 v[40:41], v5 offset0:148 offset1:156
	ds_read2_b32 v[72:73], v5 offset0:181 offset1:189
	ds_read2_b32 v[74:75], v5 offset0:214 offset1:222
	ds_read2_b32 v[78:79], v5 offset0:247 offset1:255
	v_lshl_add_u64 v[30:31], v[76:77], 0, v[2:3]
	v_lshlrev_b32_e32 v2, 1, v8
	global_store_dwordx4 v[30:31], v[26:29], off nt
	v_lshl_add_u64 v[30:31], v[76:77], 0, v[2:3]
	v_lshlrev_b32_e32 v2, 1, v10
	s_waitcnt lgkmcnt(6)
	v_cvt_pk_bf16_f32 v26, v34, v32
	s_waitcnt lgkmcnt(4)
	v_cvt_pk_bf16_f32 v27, v36, v38
	s_waitcnt lgkmcnt(2)
	v_cvt_pk_bf16_f32 v28, v40, v72
	s_waitcnt lgkmcnt(0)
	v_cvt_pk_bf16_f32 v29, v74, v78
	global_store_dwordx4 v[30:31], v[26:29], off nt
	v_lshl_add_u64 v[30:31], v[76:77], 0, v[2:3]
	s_nop 0
	v_cvt_pk_bf16_f32 v26, v35, v33
	v_cvt_pk_bf16_f32 v27, v37, v39
	v_cvt_pk_bf16_f32 v28, v41, v73
	v_cvt_pk_bf16_f32 v29, v75, v79
	global_store_dwordx4 v[30:31], v[26:29], off nt
	s_waitcnt lgkmcnt(0)
	s_branch .LBB0_158
